# mini-GEMM k-loops software pipelined: 11 operand sets in flight with counted vmcnt (was load pair, vmcnt(0), MFMA)
# baseline (speedup 1.0000x reference)
; #define MFMA32(a, b, c) __builtin_amdgcn_mfma_f32_32x32x16_bf16((a), (b), (c), 0, 0, 0)
; template <class F>
; __device__ __forceinline__ void mini_gemm(Ctx& C, const bf16* A, int lda, const bf16* Bt, int K, LAS unsigned char* lds, const F& epi) {
;     ...
;     for (int tile = C.bid; tile < 256; tile += C.G) {
;         const int tm = tile >> 4, tn = tile & 15;
;         const int row0 = MP + 64 * tm + 32 * sm, col0 = 64 * tn + 32 * sn, kh0 = kh * (K >> 1);
;         const bf16* pa = A + (size_t)(row0 + r) * lda + kh0 + 8 * hi;
;         const bf16* pb = Bt + (size_t)(col0 + r) * K + kh0 + 8 * hi;
;         f32x16 acc;
; #pragma unroll
;         for (int i = 0; i < 16; ++i) acc[i] = 0.f;
; #pragma unroll 16
;         for (int k = 0; k < (K >> 1); k += 16) acc = MFMA32(*(const s16x8*)(pa + k), *(const s16x8*)(pb + k), acc);
;         if (kh == 1) {
; #pragma unroll
;             for (int i = 0; i < 16; ++i) red[i * 64 + lane] = acc[i];
;         }
.LBB0_1004:
	s_and_b32 s13, s10, 0xffffffc0
	s_add_i32 s13, s13, s8
	s_and_b32 s14, s3, 0x3c0
	v_or_b32_e32 v0, s13, v22
	v_or_b32_e32 v20, s14, v25
	v_mad_i64_i32 v[34:35], s[14:15], v0, s61, v[16:17]
	v_lshlrev_b32_e32 v192, 10, v20
	v_lshl_add_u64 v[36:37], v[18:19], 0, v[192:193]
	s_andn2_b64 vcc, exec, s[4:5]
	global_load_dwordx4 v[126:129], v[34:35], off
	global_load_dwordx4 v[130:133], v[36:37], off
	global_load_dwordx4 v[134:137], v[34:35], off offset:32
	global_load_dwordx4 v[138:141], v[36:37], off offset:32
	global_load_dwordx4 v[142:145], v[34:35], off offset:64
	global_load_dwordx4 v[146:149], v[36:37], off offset:64
	global_load_dwordx4 v[150:153], v[34:35], off offset:96
	global_load_dwordx4 v[154:157], v[36:37], off offset:96
	global_load_dwordx4 v[158:161], v[34:35], off offset:128
	global_load_dwordx4 v[162:165], v[36:37], off offset:128
	global_load_dwordx4 v[166:169], v[34:35], off offset:160
	global_load_dwordx4 v[170:173], v[36:37], off offset:160
	global_load_dwordx4 v[174:177], v[34:35], off offset:192
	global_load_dwordx4 v[178:181], v[36:37], off offset:192
	global_load_dwordx4 v[42:45], v[34:35], off offset:224
	global_load_dwordx4 v[46:49], v[36:37], off offset:224
	global_load_dwordx4 v[50:53], v[34:35], off offset:256
	global_load_dwordx4 v[54:57], v[36:37], off offset:256
	global_load_dwordx4 v[92:95], v[34:35], off offset:288
	global_load_dwordx4 v[96:99], v[36:37], off offset:288
	global_load_dwordx4 v[100:103], v[34:35], off offset:320
	global_load_dwordx4 v[104:107], v[36:37], off offset:320
	s_waitcnt vmcnt(20)
	v_mfma_f32_32x32x16_bf16 v[0:15], v[126:129], v[130:133], 0
	global_load_dwordx4 v[126:129], v[34:35], off offset:352
	global_load_dwordx4 v[130:133], v[36:37], off offset:352
	s_waitcnt vmcnt(20)
	v_mfma_f32_32x32x16_bf16 v[0:15], v[134:137], v[138:141], v[0:15]
	global_load_dwordx4 v[134:137], v[34:35], off offset:384
	global_load_dwordx4 v[138:141], v[36:37], off offset:384
	s_waitcnt vmcnt(20)
	v_mfma_f32_32x32x16_bf16 v[0:15], v[142:145], v[146:149], v[0:15]
	global_load_dwordx4 v[142:145], v[34:35], off offset:416
	global_load_dwordx4 v[146:149], v[36:37], off offset:416
	s_waitcnt vmcnt(20)
	v_mfma_f32_32x32x16_bf16 v[0:15], v[150:153], v[154:157], v[0:15]
	global_load_dwordx4 v[150:153], v[34:35], off offset:448
	global_load_dwordx4 v[154:157], v[36:37], off offset:448
	s_waitcnt vmcnt(20)
	v_mfma_f32_32x32x16_bf16 v[0:15], v[158:161], v[162:165], v[0:15]
	global_load_dwordx4 v[158:161], v[34:35], off offset:480
	global_load_dwordx4 v[162:165], v[36:37], off offset:480
	s_waitcnt vmcnt(20)
	v_mfma_f32_32x32x16_bf16 v[0:15], v[166:169], v[170:173], v[0:15]
	s_waitcnt vmcnt(18)
	v_mfma_f32_32x32x16_bf16 v[0:15], v[174:177], v[178:181], v[0:15]
	s_waitcnt vmcnt(16)
	v_mfma_f32_32x32x16_bf16 v[0:15], v[42:45], v[46:49], v[0:15]
	s_waitcnt vmcnt(14)
	v_mfma_f32_32x32x16_bf16 v[0:15], v[50:53], v[54:57], v[0:15]
	s_waitcnt vmcnt(12)
	v_mfma_f32_32x32x16_bf16 v[0:15], v[92:95], v[96:99], v[0:15]
	s_waitcnt vmcnt(10)
	v_mfma_f32_32x32x16_bf16 v[0:15], v[100:103], v[104:107], v[0:15]
	s_waitcnt vmcnt(8)
	v_mfma_f32_32x32x16_bf16 v[0:15], v[126:129], v[130:133], v[0:15]
	s_waitcnt vmcnt(6)
	v_mfma_f32_32x32x16_bf16 v[0:15], v[134:137], v[138:141], v[0:15]
	s_waitcnt vmcnt(4)
	v_mfma_f32_32x32x16_bf16 v[0:15], v[142:145], v[146:149], v[0:15]
	s_waitcnt vmcnt(2)
	v_mfma_f32_32x32x16_bf16 v[0:15], v[150:153], v[154:157], v[0:15]
	s_waitcnt vmcnt(0)
	v_mfma_f32_32x32x16_bf16 v[0:15], v[158:161], v[162:165], v[0:15]
	s_cbranch_vccnz .LBB0_1006
	s_nop 10
	ds_write2st64_b32 v23, v0, v1 offset1:1
	ds_write2st64_b32 v23, v2, v3 offset0:2 offset1:3
	ds_write2st64_b32 v23, v4, v5 offset0:4 offset1:5
	ds_write2st64_b32 v23, v6, v7 offset0:6 offset1:7
	ds_write2st64_b32 v23, v8, v9 offset0:8 offset1:9
	ds_write2st64_b32 v23, v10, v11 offset0:10 offset1:11
	ds_write2st64_b32 v23, v12, v13 offset0:12 offset1:13
	ds_write2st64_b32 v23, v14, v15 offset0:14 offset1:15

; #define MFMA32(a, b, c) __builtin_amdgcn_mfma_f32_32x32x16_bf16((a), (b), (c), 0, 0, 0)
; template <class F>
; __device__ __forceinline__ void mini_gemm(Ctx& C, const bf16* A, int lda, const bf16* Bt, int K, LAS unsigned char* lds, const F& epi) {
;     ...
;         const int row0 = MP + 64 * tm + 32 * sm, col0 = 64 * tn + 32 * sn, kh0 = kh * (K >> 1);
;         const bf16* pa = A + (size_t)(row0 + r) * lda + kh0 + 8 * hi;
;         const bf16* pb = Bt + (size_t)(col0 + r) * K + kh0 + 8 * hi;
;         f32x16 acc;
; #pragma unroll
;         for (int i = 0; i < 16; ++i) acc[i] = 0.f;
; #pragma unroll 16
;         for (int k = 0; k < (K >> 1); k += 16) acc = MFMA32(*(const s16x8*)(pa + k), *(const s16x8*)(pb + k), acc);
;         if (kh == 1) {
; #pragma unroll
;             for (int i = 0; i < 16; ++i) red[i * 64 + lane] = acc[i];
.LBB0_1071:
	s_and_b32 s13, s10, 0xffffffc0
	s_add_i32 s13, s13, s3
	s_and_b32 s14, s8, 0x3c0
	v_or_b32_e32 v0, s13, v22
	v_or_b32_e32 v20, s14, v25
	v_mad_i64_i32 v[34:35], s[14:15], v0, s61, v[16:17]
	v_lshlrev_b32_e32 v192, 10, v20
	v_lshl_add_u64 v[36:37], v[18:19], 0, v[192:193]
	s_andn2_b64 vcc, exec, s[4:5]
	global_load_dwordx4 v[126:129], v[34:35], off
	global_load_dwordx4 v[130:133], v[36:37], off
	global_load_dwordx4 v[134:137], v[34:35], off offset:32
	global_load_dwordx4 v[138:141], v[36:37], off offset:32
	global_load_dwordx4 v[142:145], v[34:35], off offset:64
	global_load_dwordx4 v[146:149], v[36:37], off offset:64
	global_load_dwordx4 v[150:153], v[34:35], off offset:96
	global_load_dwordx4 v[154:157], v[36:37], off offset:96
	global_load_dwordx4 v[158:161], v[34:35], off offset:128
	global_load_dwordx4 v[162:165], v[36:37], off offset:128
	global_load_dwordx4 v[166:169], v[34:35], off offset:160
	global_load_dwordx4 v[170:173], v[36:37], off offset:160
	global_load_dwordx4 v[174:177], v[34:35], off offset:192
	global_load_dwordx4 v[178:181], v[36:37], off offset:192
	global_load_dwordx4 v[42:45], v[34:35], off offset:224
	global_load_dwordx4 v[46:49], v[36:37], off offset:224
	global_load_dwordx4 v[50:53], v[34:35], off offset:256
	global_load_dwordx4 v[54:57], v[36:37], off offset:256
	global_load_dwordx4 v[92:95], v[34:35], off offset:288
	global_load_dwordx4 v[96:99], v[36:37], off offset:288
	global_load_dwordx4 v[100:103], v[34:35], off offset:320
	global_load_dwordx4 v[104:107], v[36:37], off offset:320
	s_waitcnt vmcnt(20)
	v_mfma_f32_32x32x16_bf16 v[0:15], v[126:129], v[130:133], 0
	global_load_dwordx4 v[126:129], v[34:35], off offset:352
	global_load_dwordx4 v[130:133], v[36:37], off offset:352
	s_waitcnt vmcnt(20)
	v_mfma_f32_32x32x16_bf16 v[0:15], v[134:137], v[138:141], v[0:15]
	global_load_dwordx4 v[134:137], v[34:35], off offset:384
	global_load_dwordx4 v[138:141], v[36:37], off offset:384
	s_waitcnt vmcnt(20)
	v_mfma_f32_32x32x16_bf16 v[0:15], v[142:145], v[146:149], v[0:15]
	global_load_dwordx4 v[142:145], v[34:35], off offset:416
	global_load_dwordx4 v[146:149], v[36:37], off offset:416
	s_waitcnt vmcnt(20)
	v_mfma_f32_32x32x16_bf16 v[0:15], v[150:153], v[154:157], v[0:15]
	global_load_dwordx4 v[150:153], v[34:35], off offset:448
	global_load_dwordx4 v[154:157], v[36:37], off offset:448
	s_waitcnt vmcnt(20)
	v_mfma_f32_32x32x16_bf16 v[0:15], v[158:161], v[162:165], v[0:15]
	global_load_dwordx4 v[158:161], v[34:35], off offset:480
	global_load_dwordx4 v[162:165], v[36:37], off offset:480
	s_waitcnt vmcnt(20)
	v_mfma_f32_32x32x16_bf16 v[0:15], v[166:169], v[170:173], v[0:15]
	s_waitcnt vmcnt(18)
	v_mfma_f32_32x32x16_bf16 v[0:15], v[174:177], v[178:181], v[0:15]
	s_waitcnt vmcnt(16)
	v_mfma_f32_32x32x16_bf16 v[0:15], v[42:45], v[46:49], v[0:15]
	s_waitcnt vmcnt(14)
	v_mfma_f32_32x32x16_bf16 v[0:15], v[50:53], v[54:57], v[0:15]
	s_waitcnt vmcnt(12)
	v_mfma_f32_32x32x16_bf16 v[0:15], v[92:95], v[96:99], v[0:15]
	s_waitcnt vmcnt(10)
	v_mfma_f32_32x32x16_bf16 v[0:15], v[100:103], v[104:107], v[0:15]
	s_waitcnt vmcnt(8)
	v_mfma_f32_32x32x16_bf16 v[0:15], v[126:129], v[130:133], v[0:15]
	s_waitcnt vmcnt(6)
	v_mfma_f32_32x32x16_bf16 v[0:15], v[134:137], v[138:141], v[0:15]
	s_waitcnt vmcnt(4)
	v_mfma_f32_32x32x16_bf16 v[0:15], v[142:145], v[146:149], v[0:15]
	s_waitcnt vmcnt(2)
	v_mfma_f32_32x32x16_bf16 v[0:15], v[150:153], v[154:157], v[0:15]
	s_waitcnt vmcnt(0)
	v_mfma_f32_32x32x16_bf16 v[0:15], v[158:161], v[162:165], v[0:15]
	s_cbranch_vccnz .LBB0_1073
	s_nop 10
	ds_write2st64_b32 v23, v0, v1 offset1:1
	ds_write2st64_b32 v23, v2, v3 offset0:2 offset1:3
	ds_write2st64_b32 v23, v4, v5 offset0:4 offset1:5
	ds_write2st64_b32 v23, v6, v7 offset0:6 offset1:7
	ds_write2st64_b32 v23, v8, v9 offset0:8 offset1:9
	ds_write2st64_b32 v23, v10, v11 offset0:10 offset1:11
	ds_write2st64_b32 v23, v12, v13 offset0:12 offset1:13
	ds_write2st64_b32 v23, v14, v15 offset0:14 offset1:15

; #define MFMA32(a, b, c) __builtin_amdgcn_mfma_f32_32x32x16_bf16((a), (b), (c), 0, 0, 0)
; template <class F>
; __device__ __forceinline__ void mini_gemm(Ctx& C, const bf16* A, int lda, const bf16* Bt, int K, LAS unsigned char* lds, const F& epi) {
;     ...
;         const bf16* pa = A + (size_t)(row0 + r) * lda + kh0 + 8 * hi;
;         const bf16* pb = Bt + (size_t)(col0 + r) * K + kh0 + 8 * hi;
;         f32x16 acc;
; #pragma unroll
;         for (int i = 0; i < 16; ++i) acc[i] = 0.f;
; #pragma unroll 16
;         for (int k = 0; k < (K >> 1); k += 16) acc = MFMA32(*(const s16x8*)(pa + k), *(const s16x8*)(pb + k), acc);
;         if (kh == 1) {
; #pragma unroll
;             for (int i = 0; i < 16; ++i) red[i * 64 + lane] = acc[i];
.LBB0_1154:
	global_load_dwordx4 v[126:129], v[22:23], off offset:-256
	global_load_dwordx4 v[130:133], v[20:21], off offset:-256
	global_load_dwordx4 v[134:137], v[22:23], off offset:-224
	global_load_dwordx4 v[138:141], v[20:21], off offset:-224
	global_load_dwordx4 v[142:145], v[22:23], off offset:-192
	global_load_dwordx4 v[146:149], v[20:21], off offset:-192
	global_load_dwordx4 v[150:153], v[22:23], off offset:-160
	global_load_dwordx4 v[154:157], v[20:21], off offset:-160
	global_load_dwordx4 v[158:161], v[22:23], off offset:-128
	global_load_dwordx4 v[162:165], v[20:21], off offset:-128
	global_load_dwordx4 v[166:169], v[22:23], off offset:-96
	global_load_dwordx4 v[170:173], v[20:21], off offset:-96
	global_load_dwordx4 v[174:177], v[22:23], off offset:-64
	global_load_dwordx4 v[178:181], v[20:21], off offset:-64
	global_load_dwordx4 v[42:45], v[22:23], off offset:-32
	global_load_dwordx4 v[46:49], v[20:21], off offset:-32
	global_load_dwordx4 v[50:53], v[22:23], off
	global_load_dwordx4 v[54:57], v[20:21], off
	global_load_dwordx4 v[92:95], v[22:23], off offset:32
	global_load_dwordx4 v[96:99], v[20:21], off offset:32
	global_load_dwordx4 v[100:103], v[22:23], off offset:64
	global_load_dwordx4 v[104:107], v[20:21], off offset:64
	s_waitcnt vmcnt(20)
	v_mfma_f32_32x32x16_bf16 v[0:15], v[126:129], v[130:133], v[0:15]
	global_load_dwordx4 v[126:129], v[22:23], off offset:96
	global_load_dwordx4 v[130:133], v[20:21], off offset:96
	s_waitcnt vmcnt(20)
	v_mfma_f32_32x32x16_bf16 v[0:15], v[134:137], v[138:141], v[0:15]
	global_load_dwordx4 v[134:137], v[22:23], off offset:128
	global_load_dwordx4 v[138:141], v[20:21], off offset:128
	s_waitcnt vmcnt(20)
	v_mfma_f32_32x32x16_bf16 v[0:15], v[142:145], v[146:149], v[0:15]
	global_load_dwordx4 v[142:145], v[22:23], off offset:160
	global_load_dwordx4 v[146:149], v[20:21], off offset:160
	s_waitcnt vmcnt(20)
	v_mfma_f32_32x32x16_bf16 v[0:15], v[150:153], v[154:157], v[0:15]
	global_load_dwordx4 v[150:153], v[22:23], off offset:192
	global_load_dwordx4 v[154:157], v[20:21], off offset:192
	s_waitcnt vmcnt(20)
	v_mfma_f32_32x32x16_bf16 v[0:15], v[158:161], v[162:165], v[0:15]
	global_load_dwordx4 v[158:161], v[22:23], off offset:224
	global_load_dwordx4 v[162:165], v[20:21], off offset:224
	s_waitcnt vmcnt(20)
	v_mfma_f32_32x32x16_bf16 v[0:15], v[166:169], v[170:173], v[0:15]
	global_load_dwordx4 v[166:169], v[22:23], off offset:256
	global_load_dwordx4 v[170:173], v[20:21], off offset:256
	s_waitcnt vmcnt(20)
	v_mfma_f32_32x32x16_bf16 v[0:15], v[174:177], v[178:181], v[0:15]
	global_load_dwordx4 v[174:177], v[22:23], off offset:288
	global_load_dwordx4 v[178:181], v[20:21], off offset:288
	s_waitcnt vmcnt(20)
	v_mfma_f32_32x32x16_bf16 v[0:15], v[42:45], v[46:49], v[0:15]
	global_load_dwordx4 v[42:45], v[22:23], off offset:320
	global_load_dwordx4 v[46:49], v[20:21], off offset:320
	s_waitcnt vmcnt(20)
	v_mfma_f32_32x32x16_bf16 v[0:15], v[50:53], v[54:57], v[0:15]
	global_load_dwordx4 v[50:53], v[22:23], off offset:352
	global_load_dwordx4 v[54:57], v[20:21], off offset:352
	s_waitcnt vmcnt(20)
	v_mfma_f32_32x32x16_bf16 v[0:15], v[92:95], v[96:99], v[0:15]
	global_load_dwordx4 v[92:95], v[22:23], off offset:384
	global_load_dwordx4 v[96:99], v[20:21], off offset:384
	s_waitcnt vmcnt(20)
	v_mfma_f32_32x32x16_bf16 v[0:15], v[100:103], v[104:107], v[0:15]
	global_load_dwordx4 v[100:103], v[22:23], off offset:416
	global_load_dwordx4 v[104:107], v[20:21], off offset:416
	s_waitcnt vmcnt(20)
	v_mfma_f32_32x32x16_bf16 v[0:15], v[126:129], v[130:133], v[0:15]
	global_load_dwordx4 v[126:129], v[22:23], off offset:448
	global_load_dwordx4 v[130:133], v[20:21], off offset:448
	s_waitcnt vmcnt(20)
	v_mfma_f32_32x32x16_bf16 v[0:15], v[134:137], v[138:141], v[0:15]
	global_load_dwordx4 v[134:137], v[22:23], off offset:480
	global_load_dwordx4 v[138:141], v[20:21], off offset:480
	s_waitcnt vmcnt(20)
	v_mfma_f32_32x32x16_bf16 v[0:15], v[142:145], v[146:149], v[0:15]
	global_load_dwordx4 v[142:145], v[22:23], off offset:512
	global_load_dwordx4 v[146:149], v[20:21], off offset:512
	s_waitcnt vmcnt(20)
	v_mfma_f32_32x32x16_bf16 v[0:15], v[150:153], v[154:157], v[0:15]
	global_load_dwordx4 v[150:153], v[22:23], off offset:544
	global_load_dwordx4 v[154:157], v[20:21], off offset:544
	s_waitcnt vmcnt(20)
	v_mfma_f32_32x32x16_bf16 v[0:15], v[158:161], v[162:165], v[0:15]
	global_load_dwordx4 v[158:161], v[22:23], off offset:576
	global_load_dwordx4 v[162:165], v[20:21], off offset:576
	s_waitcnt vmcnt(20)
	v_mfma_f32_32x32x16_bf16 v[0:15], v[166:169], v[170:173], v[0:15]
	global_load_dwordx4 v[166:169], v[22:23], off offset:608
	global_load_dwordx4 v[170:173], v[20:21], off offset:608
	s_waitcnt vmcnt(20)
	v_mfma_f32_32x32x16_bf16 v[0:15], v[174:177], v[178:181], v[0:15]
	global_load_dwordx4 v[174:177], v[22:23], off offset:640
	global_load_dwordx4 v[178:181], v[20:21], off offset:640
	s_waitcnt vmcnt(20)
	v_mfma_f32_32x32x16_bf16 v[0:15], v[42:45], v[46:49], v[0:15]
	global_load_dwordx4 v[42:45], v[22:23], off offset:672
	global_load_dwordx4 v[46:49], v[20:21], off offset:672
	s_waitcnt vmcnt(20)
	v_mfma_f32_32x32x16_bf16 v[0:15], v[50:53], v[54:57], v[0:15]
	global_load_dwordx4 v[50:53], v[22:23], off offset:704
	global_load_dwordx4 v[54:57], v[20:21], off offset:704
	s_waitcnt vmcnt(20)
	v_mfma_f32_32x32x16_bf16 v[0:15], v[92:95], v[96:99], v[0:15]
	global_load_dwordx4 v[92:95], v[22:23], off offset:736
	global_load_dwordx4 v[96:99], v[20:21], off offset:736
	s_waitcnt vmcnt(20)
	v_mfma_f32_32x32x16_bf16 v[0:15], v[100:103], v[104:107], v[0:15]
	s_waitcnt vmcnt(18)
	v_mfma_f32_32x32x16_bf16 v[0:15], v[126:129], v[130:133], v[0:15]
	s_waitcnt vmcnt(16)
	v_mfma_f32_32x32x16_bf16 v[0:15], v[134:137], v[138:141], v[0:15]
	s_waitcnt vmcnt(14)
	v_mfma_f32_32x32x16_bf16 v[0:15], v[142:145], v[146:149], v[0:15]
	s_waitcnt vmcnt(12)
	v_mfma_f32_32x32x16_bf16 v[0:15], v[150:153], v[154:157], v[0:15]
	s_waitcnt vmcnt(10)
	v_mfma_f32_32x32x16_bf16 v[0:15], v[158:161], v[162:165], v[0:15]
	s_waitcnt vmcnt(8)
	v_mfma_f32_32x32x16_bf16 v[0:15], v[166:169], v[170:173], v[0:15]
	s_waitcnt vmcnt(6)
	v_mfma_f32_32x32x16_bf16 v[0:15], v[174:177], v[178:181], v[0:15]
	s_waitcnt vmcnt(4)
	v_mfma_f32_32x32x16_bf16 v[0:15], v[42:45], v[46:49], v[0:15]
	s_waitcnt vmcnt(2)
	v_mfma_f32_32x32x16_bf16 v[0:15], v[50:53], v[54:57], v[0:15]
	s_waitcnt vmcnt(0)
	v_mfma_f32_32x32x16_bf16 v[0:15], v[92:95], v[96:99], v[0:15]
	s_andn2_b64 vcc, exec, s[6:7]
	s_cbranch_vccnz .LBB0_1157
	s_nop 8
	ds_write2st64_b32 v26, v0, v1 offset1:1
	ds_write2st64_b32 v26, v2, v3 offset0:2 offset1:3
	ds_write2st64_b32 v26, v4, v5 offset0:4 offset1:5
	ds_write2st64_b32 v26, v6, v7 offset0:6 offset1:7
	ds_write2st64_b32 v26, v8, v9 offset0:8 offset1:9
	ds_write2st64_b32 v26, v10, v11 offset0:10 offset1:11
	ds_write2st64_b32 v26, v12, v13 offset0:12 offset1:13
	ds_write2st64_b32 v26, v14, v15 offset0:14 offset1:15

; #define MFMA32(a, b, c) __builtin_amdgcn_mfma_f32_32x32x16_bf16((a), (b), (c), 0, 0, 0)
; template <class F>
; __device__ __forceinline__ void mini_gemm(Ctx& C, const bf16* A, int lda, const bf16* Bt, int K, LAS unsigned char* lds, const F& epi) {
;     ...
;         const bf16* pa = A + (size_t)(row0 + r) * lda + kh0 + 8 * hi;
;         const bf16* pb = Bt + (size_t)(col0 + r) * K + kh0 + 8 * hi;
;         f32x16 acc;
; #pragma unroll
;         for (int i = 0; i < 16; ++i) acc[i] = 0.f;
; #pragma unroll 16
;         for (int k = 0; k < (K >> 1); k += 16) acc = MFMA32(*(const s16x8*)(pa + k), *(const s16x8*)(pb + k), acc);
.LBB0_1421:
	s_and_b32 s15, s12, 0xffffffc0
	s_and_b32 s16, s3, 0x3c0
	s_add_i32 s15, s15, s10
	v_or_b32_e32 v24, s16, v30
	v_or_b32_e32 v0, s15, v26
	v_mul_u32_u24_e32 v1, 0xb00, v24
	s_movk_i32 s16, 0x1600
	v_mad_i64_i32 v[22:23], s[16:17], v0, s16, v[16:17]
	v_lshlrev_b32_e32 v192, 1, v1
	v_lshl_add_u64 v[20:21], v[18:19], 0, v[192:193]
	s_andn2_b64 vcc, exec, s[4:5]
	s_nop 0
	global_load_dwordx4 v[126:129], v[22:23], off
	global_load_dwordx4 v[130:133], v[20:21], off
	global_load_dwordx4 v[134:137], v[22:23], off offset:32
	global_load_dwordx4 v[138:141], v[20:21], off offset:32
	global_load_dwordx4 v[142:145], v[22:23], off offset:64
	global_load_dwordx4 v[146:149], v[20:21], off offset:64
	global_load_dwordx4 v[150:153], v[22:23], off offset:96
	global_load_dwordx4 v[154:157], v[20:21], off offset:96
	global_load_dwordx4 v[158:161], v[22:23], off offset:128
	global_load_dwordx4 v[162:165], v[20:21], off offset:128
	global_load_dwordx4 v[166:169], v[22:23], off offset:160
	global_load_dwordx4 v[170:173], v[20:21], off offset:160
	global_load_dwordx4 v[174:177], v[22:23], off offset:192
	global_load_dwordx4 v[178:181], v[20:21], off offset:192
	global_load_dwordx4 v[42:45], v[22:23], off offset:224
	global_load_dwordx4 v[46:49], v[20:21], off offset:224
	global_load_dwordx4 v[50:53], v[22:23], off offset:256
	global_load_dwordx4 v[54:57], v[20:21], off offset:256
	global_load_dwordx4 v[92:95], v[22:23], off offset:288
	global_load_dwordx4 v[96:99], v[20:21], off offset:288
	global_load_dwordx4 v[100:103], v[22:23], off offset:320
	global_load_dwordx4 v[104:107], v[20:21], off offset:320
	s_waitcnt vmcnt(20)
	v_mfma_f32_32x32x16_bf16 v[0:15], v[126:129], v[130:133], 0
	global_load_dwordx4 v[126:129], v[22:23], off offset:352
	global_load_dwordx4 v[130:133], v[20:21], off offset:352
	s_waitcnt vmcnt(20)
	v_mfma_f32_32x32x16_bf16 v[0:15], v[134:137], v[138:141], v[0:15]
	global_load_dwordx4 v[134:137], v[22:23], off offset:384
	global_load_dwordx4 v[138:141], v[20:21], off offset:384
	s_waitcnt vmcnt(20)
	v_mfma_f32_32x32x16_bf16 v[0:15], v[142:145], v[146:149], v[0:15]
	global_load_dwordx4 v[142:145], v[22:23], off offset:416
	global_load_dwordx4 v[146:149], v[20:21], off offset:416
	s_waitcnt vmcnt(20)
	v_mfma_f32_32x32x16_bf16 v[0:15], v[150:153], v[154:157], v[0:15]
	global_load_dwordx4 v[150:153], v[22:23], off offset:448
	global_load_dwordx4 v[154:157], v[20:21], off offset:448
	s_waitcnt vmcnt(20)
	v_mfma_f32_32x32x16_bf16 v[0:15], v[158:161], v[162:165], v[0:15]
	global_load_dwordx4 v[158:161], v[22:23], off offset:480
	global_load_dwordx4 v[162:165], v[20:21], off offset:480
	s_waitcnt vmcnt(20)
	v_mfma_f32_32x32x16_bf16 v[0:15], v[166:169], v[170:173], v[0:15]
	global_load_dwordx4 v[166:169], v[22:23], off offset:512
	global_load_dwordx4 v[170:173], v[20:21], off offset:512
	s_waitcnt vmcnt(20)
	v_mfma_f32_32x32x16_bf16 v[0:15], v[174:177], v[178:181], v[0:15]
	global_load_dwordx4 v[174:177], v[22:23], off offset:544
	global_load_dwordx4 v[178:181], v[20:21], off offset:544
	s_waitcnt vmcnt(20)
	v_mfma_f32_32x32x16_bf16 v[0:15], v[42:45], v[46:49], v[0:15]
	global_load_dwordx4 v[42:45], v[22:23], off offset:576
	global_load_dwordx4 v[46:49], v[20:21], off offset:576
	s_waitcnt vmcnt(20)
	v_mfma_f32_32x32x16_bf16 v[0:15], v[50:53], v[54:57], v[0:15]
	global_load_dwordx4 v[50:53], v[22:23], off offset:608
	global_load_dwordx4 v[54:57], v[20:21], off offset:608
	s_waitcnt vmcnt(20)
	v_mfma_f32_32x32x16_bf16 v[0:15], v[92:95], v[96:99], v[0:15]
	global_load_dwordx4 v[92:95], v[22:23], off offset:640
	global_load_dwordx4 v[96:99], v[20:21], off offset:640
	s_waitcnt vmcnt(20)
	v_mfma_f32_32x32x16_bf16 v[0:15], v[100:103], v[104:107], v[0:15]
	global_load_dwordx4 v[100:103], v[22:23], off offset:672
	global_load_dwordx4 v[104:107], v[20:21], off offset:672
	s_waitcnt vmcnt(20)
	v_mfma_f32_32x32x16_bf16 v[0:15], v[126:129], v[130:133], v[0:15]
	global_load_dwordx4 v[126:129], v[22:23], off offset:704
	global_load_dwordx4 v[130:133], v[20:21], off offset:704
	s_waitcnt vmcnt(20)
	v_mfma_f32_32x32x16_bf16 v[0:15], v[134:137], v[138:141], v[0:15]
	global_load_dwordx4 v[134:137], v[22:23], off offset:736
	global_load_dwordx4 v[138:141], v[20:21], off offset:736
	s_waitcnt vmcnt(20)
	v_mfma_f32_32x32x16_bf16 v[0:15], v[142:145], v[146:149], v[0:15]
	global_load_dwordx4 v[142:145], v[22:23], off offset:768
	global_load_dwordx4 v[146:149], v[20:21], off offset:768
	s_waitcnt vmcnt(20)
	v_mfma_f32_32x32x16_bf16 v[0:15], v[150:153], v[154:157], v[0:15]
	global_load_dwordx4 v[150:153], v[22:23], off offset:800
	global_load_dwordx4 v[154:157], v[20:21], off offset:800
	s_waitcnt vmcnt(20)
	v_mfma_f32_32x32x16_bf16 v[0:15], v[158:161], v[162:165], v[0:15]
	global_load_dwordx4 v[158:161], v[22:23], off offset:832
	global_load_dwordx4 v[162:165], v[20:21], off offset:832
	s_waitcnt vmcnt(20)
	v_mfma_f32_32x32x16_bf16 v[0:15], v[166:169], v[170:173], v[0:15]
	global_load_dwordx4 v[166:169], v[22:23], off offset:864
	global_load_dwordx4 v[170:173], v[20:21], off offset:864
	s_waitcnt vmcnt(20)
	v_mfma_f32_32x32x16_bf16 v[0:15], v[174:177], v[178:181], v[0:15]
	global_load_dwordx4 v[174:177], v[22:23], off offset:896
	global_load_dwordx4 v[178:181], v[20:21], off offset:896
	s_waitcnt vmcnt(20)
	v_mfma_f32_32x32x16_bf16 v[0:15], v[42:45], v[46:49], v[0:15]
	global_load_dwordx4 v[42:45], v[22:23], off offset:928
	global_load_dwordx4 v[46:49], v[20:21], off offset:928
	s_waitcnt vmcnt(20)
	v_mfma_f32_32x32x16_bf16 v[0:15], v[50:53], v[54:57], v[0:15]
	global_load_dwordx4 v[50:53], v[22:23], off offset:960
	global_load_dwordx4 v[54:57], v[20:21], off offset:960
	s_waitcnt vmcnt(20)
; #define MFMA32(a, b, c) __builtin_amdgcn_mfma_f32_32x32x16_bf16((a), (b), (c), 0, 0, 0)
; template <class F>
; __device__ __forceinline__ void mini_gemm(Ctx& C, const bf16* A, int lda, const bf16* Bt, int K, LAS unsigned char* lds, const F& epi) {
;     ...
;         const bf16* pa = A + (size_t)(row0 + r) * lda + kh0 + 8 * hi;
;         const bf16* pb = Bt + (size_t)(col0 + r) * K + kh0 + 8 * hi;
;         f32x16 acc;
; #pragma unroll
;         for (int i = 0; i < 16; ++i) acc[i] = 0.f;
; #pragma unroll 16
;         for (int k = 0; k < (K >> 1); k += 16) acc = MFMA32(*(const s16x8*)(pa + k), *(const s16x8*)(pb + k), acc);
	v_mfma_f32_32x32x16_bf16 v[0:15], v[92:95], v[96:99], v[0:15]
	global_load_dwordx4 v[92:95], v[22:23], off offset:992
	global_load_dwordx4 v[96:99], v[20:21], off offset:992
	s_waitcnt vmcnt(20)
	v_mfma_f32_32x32x16_bf16 v[0:15], v[100:103], v[104:107], v[0:15]
	global_load_dwordx4 v[100:103], v[22:23], off offset:1024
	global_load_dwordx4 v[104:107], v[20:21], off offset:1024
	s_waitcnt vmcnt(20)
	v_mfma_f32_32x32x16_bf16 v[0:15], v[126:129], v[130:133], v[0:15]
	global_load_dwordx4 v[126:129], v[22:23], off offset:1056
	global_load_dwordx4 v[130:133], v[20:21], off offset:1056
	s_waitcnt vmcnt(20)
	v_mfma_f32_32x32x16_bf16 v[0:15], v[134:137], v[138:141], v[0:15]
	global_load_dwordx4 v[134:137], v[22:23], off offset:1088
	global_load_dwordx4 v[138:141], v[20:21], off offset:1088
	s_waitcnt vmcnt(20)
	v_mfma_f32_32x32x16_bf16 v[0:15], v[142:145], v[146:149], v[0:15]
	global_load_dwordx4 v[142:145], v[22:23], off offset:1120
	global_load_dwordx4 v[146:149], v[20:21], off offset:1120
	s_waitcnt vmcnt(20)
	v_mfma_f32_32x32x16_bf16 v[0:15], v[150:153], v[154:157], v[0:15]
	global_load_dwordx4 v[150:153], v[22:23], off offset:1152
	global_load_dwordx4 v[154:157], v[20:21], off offset:1152
	s_waitcnt vmcnt(20)
	v_mfma_f32_32x32x16_bf16 v[0:15], v[158:161], v[162:165], v[0:15]
	global_load_dwordx4 v[158:161], v[22:23], off offset:1184
	global_load_dwordx4 v[162:165], v[20:21], off offset:1184
	s_waitcnt vmcnt(20)
	v_mfma_f32_32x32x16_bf16 v[0:15], v[166:169], v[170:173], v[0:15]
	global_load_dwordx4 v[166:169], v[22:23], off offset:1216
	global_load_dwordx4 v[170:173], v[20:21], off offset:1216
	s_waitcnt vmcnt(20)
	v_mfma_f32_32x32x16_bf16 v[0:15], v[174:177], v[178:181], v[0:15]
	global_load_dwordx4 v[174:177], v[22:23], off offset:1248
	global_load_dwordx4 v[178:181], v[20:21], off offset:1248
	s_waitcnt vmcnt(20)
	v_mfma_f32_32x32x16_bf16 v[0:15], v[42:45], v[46:49], v[0:15]
	global_load_dwordx4 v[42:45], v[22:23], off offset:1280
	global_load_dwordx4 v[46:49], v[20:21], off offset:1280
	s_waitcnt vmcnt(20)
	v_mfma_f32_32x32x16_bf16 v[0:15], v[50:53], v[54:57], v[0:15]
	global_load_dwordx4 v[50:53], v[22:23], off offset:1312
	global_load_dwordx4 v[54:57], v[20:21], off offset:1312
	s_waitcnt vmcnt(20)
	v_mfma_f32_32x32x16_bf16 v[0:15], v[92:95], v[96:99], v[0:15]
	global_load_dwordx4 v[92:95], v[22:23], off offset:1344
	global_load_dwordx4 v[96:99], v[20:21], off offset:1344
	s_waitcnt vmcnt(20)
	v_mfma_f32_32x32x16_bf16 v[0:15], v[100:103], v[104:107], v[0:15]
	global_load_dwordx4 v[100:103], v[22:23], off offset:1376
	global_load_dwordx4 v[104:107], v[20:21], off offset:1376
	s_waitcnt vmcnt(20)
	v_mfma_f32_32x32x16_bf16 v[0:15], v[126:129], v[130:133], v[0:15]
	global_load_dwordx4 v[126:129], v[22:23], off offset:1408
	global_load_dwordx4 v[130:133], v[20:21], off offset:1408
	s_waitcnt vmcnt(20)
	v_mfma_f32_32x32x16_bf16 v[0:15], v[134:137], v[138:141], v[0:15]
	global_load_dwordx4 v[134:137], v[22:23], off offset:1440
	global_load_dwordx4 v[138:141], v[20:21], off offset:1440
	s_waitcnt vmcnt(20)
	v_mfma_f32_32x32x16_bf16 v[0:15], v[142:145], v[146:149], v[0:15]
	global_load_dwordx4 v[142:145], v[22:23], off offset:1472
	global_load_dwordx4 v[146:149], v[20:21], off offset:1472
	s_waitcnt vmcnt(20)
	v_mfma_f32_32x32x16_bf16 v[0:15], v[150:153], v[154:157], v[0:15]
	global_load_dwordx4 v[150:153], v[22:23], off offset:1504
	global_load_dwordx4 v[154:157], v[20:21], off offset:1504
	s_waitcnt vmcnt(20)
	v_mfma_f32_32x32x16_bf16 v[0:15], v[158:161], v[162:165], v[0:15]
	global_load_dwordx4 v[158:161], v[22:23], off offset:1536
	global_load_dwordx4 v[162:165], v[20:21], off offset:1536
	s_waitcnt vmcnt(20)
	v_mfma_f32_32x32x16_bf16 v[0:15], v[166:169], v[170:173], v[0:15]
	global_load_dwordx4 v[166:169], v[22:23], off offset:1568
	global_load_dwordx4 v[170:173], v[20:21], off offset:1568
	s_waitcnt vmcnt(20)
	v_mfma_f32_32x32x16_bf16 v[0:15], v[174:177], v[178:181], v[0:15]
	global_load_dwordx4 v[174:177], v[22:23], off offset:1600
	global_load_dwordx4 v[178:181], v[20:21], off offset:1600
	s_waitcnt vmcnt(20)
	v_mfma_f32_32x32x16_bf16 v[0:15], v[42:45], v[46:49], v[0:15]
	global_load_dwordx4 v[42:45], v[22:23], off offset:1632
	global_load_dwordx4 v[46:49], v[20:21], off offset:1632
	s_waitcnt vmcnt(20)
	v_mfma_f32_32x32x16_bf16 v[0:15], v[50:53], v[54:57], v[0:15]
	global_load_dwordx4 v[50:53], v[22:23], off offset:1664
	global_load_dwordx4 v[54:57], v[20:21], off offset:1664
	s_waitcnt vmcnt(20)
	v_mfma_f32_32x32x16_bf16 v[0:15], v[92:95], v[96:99], v[0:15]
	global_load_dwordx4 v[92:95], v[22:23], off offset:1696
	global_load_dwordx4 v[96:99], v[20:21], off offset:1696
	s_waitcnt vmcnt(20)
	v_mfma_f32_32x32x16_bf16 v[0:15], v[100:103], v[104:107], v[0:15]
	global_load_dwordx4 v[100:103], v[22:23], off offset:1728
	global_load_dwordx4 v[104:107], v[20:21], off offset:1728
	s_waitcnt vmcnt(20)
	v_mfma_f32_32x32x16_bf16 v[0:15], v[126:129], v[130:133], v[0:15]
	global_load_dwordx4 v[126:129], v[22:23], off offset:1760
	global_load_dwordx4 v[130:133], v[20:21], off offset:1760
	s_waitcnt vmcnt(20)
	v_mfma_f32_32x32x16_bf16 v[0:15], v[134:137], v[138:141], v[0:15]
	global_load_dwordx4 v[134:137], v[22:23], off offset:1792
	global_load_dwordx4 v[138:141], v[20:21], off offset:1792
	s_waitcnt vmcnt(20)
	v_mfma_f32_32x32x16_bf16 v[0:15], v[142:145], v[146:149], v[0:15]
	global_load_dwordx4 v[142:145], v[22:23], off offset:1824
	global_load_dwordx4 v[146:149], v[20:21], off offset:1824
	s_waitcnt vmcnt(20)
	v_mfma_f32_32x32x16_bf16 v[0:15], v[150:153], v[154:157], v[0:15]
	global_load_dwordx4 v[150:153], v[22:23], off offset:1856
	global_load_dwordx4 v[154:157], v[20:21], off offset:1856
	s_waitcnt vmcnt(20)
; #define MFMA32(a, b, c) __builtin_amdgcn_mfma_f32_32x32x16_bf16((a), (b), (c), 0, 0, 0)
; template <class F>
; __device__ __forceinline__ void mini_gemm(Ctx& C, const bf16* A, int lda, const bf16* Bt, int K, LAS unsigned char* lds, const F& epi) {
;     ...
;         const bf16* pa = A + (size_t)(row0 + r) * lda + kh0 + 8 * hi;
;         const bf16* pb = Bt + (size_t)(col0 + r) * K + kh0 + 8 * hi;
;         f32x16 acc;
; #pragma unroll
;         for (int i = 0; i < 16; ++i) acc[i] = 0.f;
; #pragma unroll 16
;         for (int k = 0; k < (K >> 1); k += 16) acc = MFMA32(*(const s16x8*)(pa + k), *(const s16x8*)(pb + k), acc);
	v_mfma_f32_32x32x16_bf16 v[0:15], v[158:161], v[162:165], v[0:15]
	global_load_dwordx4 v[158:161], v[22:23], off offset:1888
	global_load_dwordx4 v[162:165], v[20:21], off offset:1888
	s_waitcnt vmcnt(20)
	v_mfma_f32_32x32x16_bf16 v[0:15], v[166:169], v[170:173], v[0:15]
	global_load_dwordx4 v[166:169], v[22:23], off offset:1920
	global_load_dwordx4 v[170:173], v[20:21], off offset:1920
	s_waitcnt vmcnt(20)
	v_mfma_f32_32x32x16_bf16 v[0:15], v[174:177], v[178:181], v[0:15]
	global_load_dwordx4 v[174:177], v[22:23], off offset:1952
	global_load_dwordx4 v[178:181], v[20:21], off offset:1952
	s_waitcnt vmcnt(20)
	v_mfma_f32_32x32x16_bf16 v[0:15], v[42:45], v[46:49], v[0:15]
	global_load_dwordx4 v[42:45], v[22:23], off offset:1984
	global_load_dwordx4 v[46:49], v[20:21], off offset:1984
	s_waitcnt vmcnt(20)
	v_mfma_f32_32x32x16_bf16 v[0:15], v[50:53], v[54:57], v[0:15]
	global_load_dwordx4 v[50:53], v[22:23], off offset:2016
	global_load_dwordx4 v[54:57], v[20:21], off offset:2016
	s_waitcnt vmcnt(20)
	v_mfma_f32_32x32x16_bf16 v[0:15], v[92:95], v[96:99], v[0:15]
	global_load_dwordx4 v[92:95], v[22:23], off offset:2048
	global_load_dwordx4 v[96:99], v[20:21], off offset:2048
	s_waitcnt vmcnt(20)
	v_mfma_f32_32x32x16_bf16 v[0:15], v[100:103], v[104:107], v[0:15]
	global_load_dwordx4 v[100:103], v[22:23], off offset:2080
	global_load_dwordx4 v[104:107], v[20:21], off offset:2080
	s_waitcnt vmcnt(20)
	v_mfma_f32_32x32x16_bf16 v[0:15], v[126:129], v[130:133], v[0:15]
	global_load_dwordx4 v[126:129], v[22:23], off offset:2112
	global_load_dwordx4 v[130:133], v[20:21], off offset:2112
	s_waitcnt vmcnt(20)
	v_mfma_f32_32x32x16_bf16 v[0:15], v[134:137], v[138:141], v[0:15]
	global_load_dwordx4 v[134:137], v[22:23], off offset:2144
	global_load_dwordx4 v[138:141], v[20:21], off offset:2144
	s_waitcnt vmcnt(20)
	v_mfma_f32_32x32x16_bf16 v[0:15], v[142:145], v[146:149], v[0:15]
	global_load_dwordx4 v[142:145], v[22:23], off offset:2176
	global_load_dwordx4 v[146:149], v[20:21], off offset:2176
	s_waitcnt vmcnt(20)
	v_mfma_f32_32x32x16_bf16 v[0:15], v[150:153], v[154:157], v[0:15]
	global_load_dwordx4 v[150:153], v[22:23], off offset:2208
	global_load_dwordx4 v[154:157], v[20:21], off offset:2208
	s_waitcnt vmcnt(20)
	v_mfma_f32_32x32x16_bf16 v[0:15], v[158:161], v[162:165], v[0:15]
	global_load_dwordx4 v[158:161], v[22:23], off offset:2240
	global_load_dwordx4 v[162:165], v[20:21], off offset:2240
	s_waitcnt vmcnt(20)
	v_mfma_f32_32x32x16_bf16 v[0:15], v[166:169], v[170:173], v[0:15]
	global_load_dwordx4 v[166:169], v[22:23], off offset:2272
	global_load_dwordx4 v[170:173], v[20:21], off offset:2272
	s_waitcnt vmcnt(20)
	v_mfma_f32_32x32x16_bf16 v[0:15], v[174:177], v[178:181], v[0:15]
	global_load_dwordx4 v[174:177], v[22:23], off offset:2304
	global_load_dwordx4 v[178:181], v[20:21], off offset:2304
	s_waitcnt vmcnt(20)
	v_mfma_f32_32x32x16_bf16 v[0:15], v[42:45], v[46:49], v[0:15]
	global_load_dwordx4 v[42:45], v[22:23], off offset:2336
	global_load_dwordx4 v[46:49], v[20:21], off offset:2336
	s_waitcnt vmcnt(20)
	v_mfma_f32_32x32x16_bf16 v[0:15], v[50:53], v[54:57], v[0:15]
	global_load_dwordx4 v[50:53], v[22:23], off offset:2368
	global_load_dwordx4 v[54:57], v[20:21], off offset:2368
	s_waitcnt vmcnt(20)
	v_mfma_f32_32x32x16_bf16 v[0:15], v[92:95], v[96:99], v[0:15]
	global_load_dwordx4 v[92:95], v[22:23], off offset:2400
	global_load_dwordx4 v[96:99], v[20:21], off offset:2400
	s_waitcnt vmcnt(20)
	v_mfma_f32_32x32x16_bf16 v[0:15], v[100:103], v[104:107], v[0:15]
	global_load_dwordx4 v[100:103], v[22:23], off offset:2432
	global_load_dwordx4 v[104:107], v[20:21], off offset:2432
	s_waitcnt vmcnt(20)
	v_mfma_f32_32x32x16_bf16 v[0:15], v[126:129], v[130:133], v[0:15]
	global_load_dwordx4 v[126:129], v[22:23], off offset:2464
	global_load_dwordx4 v[130:133], v[20:21], off offset:2464
	s_waitcnt vmcnt(20)
	v_mfma_f32_32x32x16_bf16 v[0:15], v[134:137], v[138:141], v[0:15]
	global_load_dwordx4 v[134:137], v[22:23], off offset:2496
	global_load_dwordx4 v[138:141], v[20:21], off offset:2496
	s_waitcnt vmcnt(20)
	v_mfma_f32_32x32x16_bf16 v[0:15], v[142:145], v[146:149], v[0:15]
	global_load_dwordx4 v[142:145], v[22:23], off offset:2528
	global_load_dwordx4 v[146:149], v[20:21], off offset:2528
	s_waitcnt vmcnt(20)
	v_mfma_f32_32x32x16_bf16 v[0:15], v[150:153], v[154:157], v[0:15]
	global_load_dwordx4 v[150:153], v[22:23], off offset:2560
	global_load_dwordx4 v[154:157], v[20:21], off offset:2560
	s_waitcnt vmcnt(20)
	v_mfma_f32_32x32x16_bf16 v[0:15], v[158:161], v[162:165], v[0:15]
	global_load_dwordx4 v[158:161], v[22:23], off offset:2592
	global_load_dwordx4 v[162:165], v[20:21], off offset:2592
	s_waitcnt vmcnt(20)
	v_mfma_f32_32x32x16_bf16 v[0:15], v[166:169], v[170:173], v[0:15]
	global_load_dwordx4 v[166:169], v[22:23], off offset:2624
	global_load_dwordx4 v[170:173], v[20:21], off offset:2624
	s_waitcnt vmcnt(20)
	v_mfma_f32_32x32x16_bf16 v[0:15], v[174:177], v[178:181], v[0:15]
	global_load_dwordx4 v[174:177], v[22:23], off offset:2656
	global_load_dwordx4 v[178:181], v[20:21], off offset:2656
	s_waitcnt vmcnt(20)
	v_mfma_f32_32x32x16_bf16 v[0:15], v[42:45], v[46:49], v[0:15]
	global_load_dwordx4 v[42:45], v[22:23], off offset:2688
	global_load_dwordx4 v[46:49], v[20:21], off offset:2688
	s_waitcnt vmcnt(20)
	v_mfma_f32_32x32x16_bf16 v[0:15], v[50:53], v[54:57], v[0:15]
	global_load_dwordx4 v[50:53], v[22:23], off offset:2720
	global_load_dwordx4 v[54:57], v[20:21], off offset:2720
	s_waitcnt vmcnt(20)
	v_mfma_f32_32x32x16_bf16 v[0:15], v[92:95], v[96:99], v[0:15]
	global_load_dwordx4 v[92:95], v[22:23], off offset:2752
	global_load_dwordx4 v[96:99], v[20:21], off offset:2752
	s_waitcnt vmcnt(20)
	v_mfma_f32_32x32x16_bf16 v[0:15], v[100:103], v[104:107], v[0:15]
	global_load_dwordx4 v[100:103], v[22:23], off offset:2784
	global_load_dwordx4 v[104:107], v[20:21], off offset:2784
	s_waitcnt vmcnt(20)
	v_mfma_f32_32x32x16_bf16 v[0:15], v[126:129], v[130:133], v[0:15]
	s_waitcnt vmcnt(18)
	v_mfma_f32_32x32x16_bf16 v[0:15], v[134:137], v[138:141], v[0:15]
	s_waitcnt vmcnt(16)
	v_mfma_f32_32x32x16_bf16 v[0:15], v[142:145], v[146:149], v[0:15]
	s_waitcnt vmcnt(14)
	v_mfma_f32_32x32x16_bf16 v[0:15], v[150:153], v[154:157], v[0:15]
	s_waitcnt vmcnt(12)
	v_mfma_f32_32x32x16_bf16 v[0:15], v[158:161], v[162:165], v[0:15]
	s_waitcnt vmcnt(10)
	v_mfma_f32_32x32x16_bf16 v[0:15], v[166:169], v[170:173], v[0:15]
	s_waitcnt vmcnt(8)
	v_mfma_f32_32x32x16_bf16 v[0:15], v[174:177], v[178:181], v[0:15]
	s_waitcnt vmcnt(6)
	v_mfma_f32_32x32x16_bf16 v[0:15], v[42:45], v[46:49], v[0:15]
	s_waitcnt vmcnt(4)
	v_mfma_f32_32x32x16_bf16 v[0:15], v[50:53], v[54:57], v[0:15]
	s_waitcnt vmcnt(2)
	v_mfma_f32_32x32x16_bf16 v[0:15], v[92:95], v[96:99], v[0:15]
	s_waitcnt vmcnt(0)
	v_mfma_f32_32x32x16_bf16 v[0:15], v[100:103], v[104:107], v[0:15]
	s_cbranch_vccnz .LBB0_1423
; template <class F>
; __device__ __forceinline__ void mini_gemm(Ctx& C, const bf16* A, int lda, const bf16* Bt, int K, LAS unsigned char* lds, const F& epi) {
;     ...
;         if (kh == 1) {
; #pragma unroll
;             for (int i = 0; i < 16; ++i) red[i * 64 + lane] = acc[i];
;         }
	s_nop 10
	ds_write2st64_b32 v27, v0, v1 offset1:1
	ds_write2st64_b32 v27, v2, v3 offset0:2 offset1:3
	ds_write2st64_b32 v27, v4, v5 offset0:4 offset1:5
	ds_write2st64_b32 v27, v6, v7 offset0:6 offset1:7
	ds_write2st64_b32 v27, v8, v9 offset0:8 offset1:9
	ds_write2st64_b32 v27, v10, v11 offset0:10 offset1:11
	ds_write2st64_b32 v27, v12, v13 offset0:12 offset1:13
	ds_write2st64_b32 v27, v14, v15 offset0:14 offset1:15
